# X57: X55 plus, in the down / w_in / w_out K-loops, constant LDS slot offsets folded into their single scalar add and the M0-to-DMA wait states filled with ds_reads instead of s_nop
# speedup vs baseline: 1.0019x; 1.0019x over previous
; #define PG8_STAGE(bufoff, gbase, voff) do { _Pragma("unroll") for (int _i = 0; _i < 2; ++_i) \
;         __builtin_amdgcn_global_load_lds((const unsigned*)((const char*)(gbase) + (voff)[_i]), (PG8_LAS unsigned*)(lds + (bufoff) + ldsw + _i * 8192), 16, 0, 0); } while (0)
; #define PG8_LDA(dst, b, h) do { _Pragma("unroll") for (int m = 0; m < 4; ++m) _Pragma("unroll") for (int k = 0; k < 2; ++k) dst[m][k] = *(const PG8_LAS bf16x8*)(lds + PG8_SA(b, h) + aoff + m * 2048 + k * 1024); } while (0)
; #define PG8_LDB(dst, b, h) do { _Pragma("unroll") for (int n = 0; n < 2; ++n) _Pragma("unroll") for (int k = 0; k < 2; ++k) dst[n][k] = *(const PG8_LAS bf16x8*)(lds + PG8_SB(b, h) + boff + n * 2048 + k * 1024); } while (0)
; #define PG8_MMA(ai, bj, At, Bt) do { __builtin_amdgcn_s_setprio(1); _Pragma("unroll") for (int m = 0; m < 4; ++m) _Pragma("unroll") for (int n = 0; n < 2; ++n) _Pragma("unroll") for (int k = 0; k < 2; ++k) \
;         acc[ai][bj][m][n] = __builtin_amdgcn_mfma_f32_16x16x32_bf16(Bt[n][k], At[m][k], acc[ai][bj][m][n], 0, 0, 0); __builtin_amdgcn_s_setprio(0); } while (0)
; #define PG8_WAIT_V(n) asm volatile("s_waitcnt vmcnt(" #n ")" ::: "memory")
; #define PG8_WAIT_L(n) asm volatile("s_waitcnt lgkmcnt(" #n ")" ::: "memory")
; #define PG8_BAR __builtin_amdgcn_s_barrier()
; #define PG8_SCHED __builtin_amdgcn_sched_barrier(0)
; template <class Epi, class Sched, bool ALIGN_EPI = false, bool SP2 = false>
; __device__ __forceinline__ void gemm_phase(PG8_LAS unsigned char* lds, const Gemm g, const Sched& S, const Epi& E) {
;     ...
;             PG8_LDB(B0, 0, 0); PG8_LDB(B1, 0, 1); PG8_SCHED; PG8_LDA(At, 0, 0); PG8_STAGE(PG8_SA(1, 1), a1 + hstep, voffA);
;             PG8_WAIT_V(8); PG8_WAIT_L(0); PG8_BAR; PG8_MMA(0, 0, At, B0); PG8_MMA(0, 1, At, B1); PG8_BAR; PG8_SCHED;
;             PG8_LDA(At, 0, 1); PG8_STAGE(PG8_SB(0, 0), b2, voffB); PG8_STAGE(PG8_SB(0, 1), b2 + hstep, voffB); PG8_STAGE(PG8_SA(0, 0), a2, voffA);
;             PG8_WAIT_V(8); PG8_WAIT_L(0); PG8_BAR; PG8_MMA(1, 0, At, B0); PG8_MMA(1, 1, At, B1); PG8_BAR; PG8_SCHED;
.LBB0_299:
	s_add_u32 s50, s22, 0x100
	s_addc_u32 s51, s23, 0
	s_cmpk_eq_i32 s20, 0x54
	s_cselect_b32 s55, s41, s51
	s_cselect_b32 s54, s40, s50
	s_cselect_b32 s53, s49, s69
	s_cselect_b32 s52, s48, s33
	ds_read_b128 v[134:137], v236
	ds_read_b128 v[138:141], v236 offset:1024
	ds_read_b128 v[142:145], v236 offset:2048
	ds_read_b128 v[146:149], v236 offset:3072
	ds_read_b128 v[150:153], v237
	ds_read_b128 v[154:157], v237 offset:1024
	ds_read_b128 v[176:179], v237 offset:2048
	ds_read_b128 v[180:183], v237 offset:3072
	s_add_i32 m0, s56, 0xc000
	ds_read_b128 v[184:187], v188
	ds_read_b128 v[190:193], v188 offset:1024
	ds_read_b128 v[212:215], v188 offset:2048
	ds_read_b128 v[216:219], v188 offset:3072
	ds_read_b128 v[220:223], v188 offset:4096
	ds_read_b128 v[224:227], v188 offset:5120
	ds_read_b128 v[228:231], v188 offset:6144
	global_load_lds_dwordx4 v172, s[22:23]
	s_add_i32 m0, s56, 0xe000
	ds_read_b128 v[232:235], v188 offset:7168
	global_load_lds_dwordx4 v174, s[22:23]
	s_waitcnt vmcnt(8)
	s_waitcnt lgkmcnt(0)
	s_barrier
	v_mfma_f32_16x16x32_bf16 v[122:125], v[134:137], v[184:187], v[122:125]
	v_mfma_f32_16x16x32_bf16 v[122:125], v[138:141], v[190:193], v[122:125]
	v_mfma_f32_16x16x32_bf16 v[118:121], v[142:145], v[184:187], v[118:121]
	v_mfma_f32_16x16x32_bf16 v[118:121], v[146:149], v[190:193], v[118:121]
	v_mfma_f32_16x16x32_bf16 v[130:133], v[150:153], v[184:187], v[130:133]
	v_mfma_f32_16x16x32_bf16 v[130:133], v[154:157], v[190:193], v[130:133]
	v_mfma_f32_16x16x32_bf16 v[126:129], v[176:179], v[184:187], v[126:129]
	v_mfma_f32_16x16x32_bf16 v[126:129], v[180:183], v[190:193], v[126:129]
	v_mfma_f32_16x16x32_bf16 v[102:105], v[176:179], v[212:215], v[102:105]
	v_mfma_f32_16x16x32_bf16 v[102:105], v[180:183], v[216:219], v[102:105]
	v_mfma_f32_16x16x32_bf16 v[106:109], v[150:153], v[212:215], v[106:109]
	v_mfma_f32_16x16x32_bf16 v[106:109], v[154:157], v[216:219], v[106:109]
	v_mfma_f32_16x16x32_bf16 v[110:113], v[142:145], v[212:215], v[110:113]
	v_mfma_f32_16x16x32_bf16 v[110:113], v[146:149], v[216:219], v[110:113]
	v_mfma_f32_16x16x32_bf16 v[114:117], v[134:137], v[212:215], v[114:117]
	v_mfma_f32_16x16x32_bf16 v[114:117], v[138:141], v[216:219], v[114:117]
	v_mfma_f32_16x16x32_bf16 v[98:101], v[134:137], v[220:223], v[98:101]
	v_mfma_f32_16x16x32_bf16 v[98:101], v[138:141], v[224:227], v[98:101]
	v_mfma_f32_16x16x32_bf16 v[94:97], v[142:145], v[220:223], v[94:97]
	v_mfma_f32_16x16x32_bf16 v[94:97], v[146:149], v[224:227], v[94:97]
	v_mfma_f32_16x16x32_bf16 v[90:93], v[150:153], v[220:223], v[90:93]
	v_mfma_f32_16x16x32_bf16 v[90:93], v[154:157], v[224:227], v[90:93]
	v_mfma_f32_16x16x32_bf16 v[86:89], v[176:179], v[220:223], v[86:89]
	v_mfma_f32_16x16x32_bf16 v[86:89], v[180:183], v[224:227], v[86:89]
	v_mfma_f32_16x16x32_bf16 v[70:73], v[176:179], v[228:231], v[70:73]
	v_mfma_f32_16x16x32_bf16 v[70:73], v[180:183], v[232:235], v[70:73]
	v_mfma_f32_16x16x32_bf16 v[74:77], v[150:153], v[228:231], v[74:77]
	v_mfma_f32_16x16x32_bf16 v[74:77], v[154:157], v[232:235], v[74:77]
	v_mfma_f32_16x16x32_bf16 v[78:81], v[142:145], v[228:231], v[78:81]
	v_mfma_f32_16x16x32_bf16 v[78:81], v[146:149], v[232:235], v[78:81]
	v_mfma_f32_16x16x32_bf16 v[82:85], v[134:137], v[228:231], v[82:85]
	v_mfma_f32_16x16x32_bf16 v[82:85], v[138:141], v[232:235], v[82:85]
	s_barrier
	s_add_i32 s4, s24, 0x10000
	s_mov_b32 m0, s4
	ds_read_b128 v[184:187], v188 offset:16384
	ds_read_b128 v[190:193], v188 offset:17408
	ds_read_b128 v[212:215], v188 offset:18432
	ds_read_b128 v[216:219], v188 offset:19456
	global_load_lds_dwordx4 v4, s[52:53]
	s_add_i32 m0, s4, 0x2000
	s_add_u32 s22, s52, 0x160000
	s_addc_u32 s23, s53, 0
	s_add_i32 s4, s24, 0x14000
	global_load_lds_dwordx4 v170, s[52:53]
	s_mov_b32 m0, s4
	ds_read_b128 v[220:223], v188 offset:20480
	global_load_lds_dwordx4 v4, s[22:23]
	s_add_i32 m0, s4, 0x2000
	ds_read_b128 v[224:227], v188 offset:21504
	global_load_lds_dwordx4 v170, s[22:23]
	s_mov_b32 m0, s56
	ds_read_b128 v[228:231], v188 offset:22528
	global_load_lds_dwordx4 v2, s[54:55]
	s_mov_b32 m0, s57
	ds_read_b128 v[232:235], v188 offset:23552
	global_load_lds_dwordx4 v168, s[54:55]
	s_waitcnt vmcnt(8)
	s_waitcnt lgkmcnt(0)
	s_barrier
	v_mfma_f32_16x16x32_bf16 v[58:61], v[134:137], v[184:187], v[58:61]
	v_mfma_f32_16x16x32_bf16 v[58:61], v[138:141], v[190:193], v[58:61]
	v_mfma_f32_16x16x32_bf16 v[54:57], v[142:145], v[184:187], v[54:57]
	v_mfma_f32_16x16x32_bf16 v[54:57], v[146:149], v[190:193], v[54:57]
	v_mfma_f32_16x16x32_bf16 v[66:69], v[150:153], v[184:187], v[66:69]
	v_mfma_f32_16x16x32_bf16 v[66:69], v[154:157], v[190:193], v[66:69]
	v_mfma_f32_16x16x32_bf16 v[62:65], v[176:179], v[184:187], v[62:65]
	v_mfma_f32_16x16x32_bf16 v[62:65], v[180:183], v[190:193], v[62:65]
	v_mfma_f32_16x16x32_bf16 v[38:41], v[176:179], v[212:215], v[38:41]
	v_mfma_f32_16x16x32_bf16 v[38:41], v[180:183], v[216:219], v[38:41]
	v_mfma_f32_16x16x32_bf16 v[42:45], v[150:153], v[212:215], v[42:45]
	v_mfma_f32_16x16x32_bf16 v[42:45], v[154:157], v[216:219], v[42:45]
	v_mfma_f32_16x16x32_bf16 v[46:49], v[142:145], v[212:215], v[46:49]
	v_mfma_f32_16x16x32_bf16 v[46:49], v[146:149], v[216:219], v[46:49]
	v_mfma_f32_16x16x32_bf16 v[50:53], v[134:137], v[212:215], v[50:53]
	v_mfma_f32_16x16x32_bf16 v[50:53], v[138:141], v[216:219], v[50:53]
	v_mfma_f32_16x16x32_bf16 v[34:37], v[134:137], v[220:223], v[34:37]
	v_mfma_f32_16x16x32_bf16 v[34:37], v[138:141], v[224:227], v[34:37]
	v_mfma_f32_16x16x32_bf16 v[30:33], v[142:145], v[220:223], v[30:33]
	v_mfma_f32_16x16x32_bf16 v[30:33], v[146:149], v[224:227], v[30:33]
	v_mfma_f32_16x16x32_bf16 v[26:29], v[150:153], v[220:223], v[26:29]
	v_mfma_f32_16x16x32_bf16 v[26:29], v[154:157], v[224:227], v[26:29]
	v_mfma_f32_16x16x32_bf16 v[22:25], v[176:179], v[220:223], v[22:25]
	v_mfma_f32_16x16x32_bf16 v[22:25], v[180:183], v[224:227], v[22:25]
	v_mfma_f32_16x16x32_bf16 v[6:9], v[176:179], v[228:231], v[6:9]
	v_mfma_f32_16x16x32_bf16 v[6:9], v[180:183], v[232:235], v[6:9]
	v_mfma_f32_16x16x32_bf16 v[10:13], v[150:153], v[228:231], v[10:13]
	v_mfma_f32_16x16x32_bf16 v[10:13], v[154:157], v[232:235], v[10:13]
	v_mfma_f32_16x16x32_bf16 v[14:17], v[142:145], v[228:231], v[14:17]
	v_mfma_f32_16x16x32_bf16 v[14:17], v[146:149], v[232:235], v[14:17]
	v_mfma_f32_16x16x32_bf16 v[18:21], v[134:137], v[228:231], v[18:21]
	v_mfma_f32_16x16x32_bf16 v[18:21], v[138:141], v[232:235], v[18:21]
	s_barrier
; #define PG8_STAGE(bufoff, gbase, voff) do { _Pragma("unroll") for (int _i = 0; _i < 2; ++_i) \
;         __builtin_amdgcn_global_load_lds((const unsigned*)((const char*)(gbase) + (voff)[_i]), (PG8_LAS unsigned*)(lds + (bufoff) + ldsw + _i * 8192), 16, 0, 0); } while (0)
; #define PG8_LDA(dst, b, h) do { _Pragma("unroll") for (int m = 0; m < 4; ++m) _Pragma("unroll") for (int k = 0; k < 2; ++k) dst[m][k] = *(const PG8_LAS bf16x8*)(lds + PG8_SA(b, h) + aoff + m * 2048 + k * 1024); } while (0)
; #define PG8_LDB(dst, b, h) do { _Pragma("unroll") for (int n = 0; n < 2; ++n) _Pragma("unroll") for (int k = 0; k < 2; ++k) dst[n][k] = *(const PG8_LAS bf16x8*)(lds + PG8_SB(b, h) + boff + n * 2048 + k * 1024); } while (0)
; #define PG8_MMA(ai, bj, At, Bt) do { __builtin_amdgcn_s_setprio(1); _Pragma("unroll") for (int m = 0; m < 4; ++m) _Pragma("unroll") for (int n = 0; n < 2; ++n) _Pragma("unroll") for (int k = 0; k < 2; ++k) \
;         acc[ai][bj][m][n] = __builtin_amdgcn_mfma_f32_16x16x32_bf16(Bt[n][k], At[m][k], acc[ai][bj][m][n], 0, 0, 0); __builtin_amdgcn_s_setprio(0); } while (0)
; #define PG8_WAIT_V(n) asm volatile("s_waitcnt vmcnt(" #n ")" ::: "memory")
; #define PG8_WAIT_L(n) asm volatile("s_waitcnt lgkmcnt(" #n ")" ::: "memory")
; #define PG8_BAR __builtin_amdgcn_s_barrier()
; #define PG8_SCHED __builtin_amdgcn_sched_barrier(0)
; template <class Epi, class Sched, bool ALIGN_EPI = false, bool SP2 = false>
; __device__ __forceinline__ void gemm_phase(PG8_LAS unsigned char* lds, const Gemm g, const Sched& S, const Epi& E) {
;     ...
;             PG8_LDB(B0, 1, 0); PG8_LDB(B1, 1, 1); PG8_SCHED; PG8_LDA(At, 1, 0); PG8_STAGE(PG8_SA(0, 1), a2 + hstep, voffA);
;             PG8_WAIT_V(8); PG8_WAIT_L(0); PG8_BAR; PG8_MMA(0, 0, At, B0); PG8_MMA(0, 1, At, B1); PG8_BAR; PG8_SCHED;
;             PG8_LDA(At, 1, 1); PG8_STAGE(PG8_SB(1, 0), b3, voffB); PG8_STAGE(PG8_SB(1, 1), b3 + hstep, voffB); PG8_STAGE(PG8_SA(1, 0), a3, voffA);
;             PG8_WAIT_V(8); PG8_WAIT_L(0); PG8_BAR; PG8_MMA(1, 0, At, B0); PG8_MMA(1, 1, At, B1); PG8_BAR; PG8_SCHED;
	s_add_i32 s5, 0, 0x1c000
	ds_read_b128 v[134:137], v238
	ds_read_b128 v[138:141], v238 offset:1024
	ds_read_b128 v[142:145], v238 offset:2048
	ds_read_b128 v[146:149], v238 offset:3072
	ds_read_b128 v[150:153], v239
	ds_read_b128 v[154:157], v239 offset:1024
	ds_read_b128 v[176:179], v239 offset:2048
	ds_read_b128 v[180:183], v239 offset:3072
	s_add_u32 s22, s54, 0x160000
	s_addc_u32 s23, s55, 0
	s_mov_b32 m0, s59
	ds_read_b128 v[184:187], v188 offset:32768
	ds_read_b128 v[190:193], v188 offset:33792
	ds_read_b128 v[212:215], v188 offset:34816
	ds_read_b128 v[216:219], v188 offset:35840
	ds_read_b128 v[220:223], v188 offset:36864
	ds_read_b128 v[224:227], v188 offset:37888
	ds_read_b128 v[228:231], v188 offset:38912
	global_load_lds_dwordx4 v2, s[22:23]
	s_mov_b32 m0, s60
	ds_read_b128 v[232:235], v188 offset:39936
	global_load_lds_dwordx4 v168, s[22:23]
	s_waitcnt vmcnt(8)
	s_waitcnt lgkmcnt(0)
	s_barrier
	v_mfma_f32_16x16x32_bf16 v[122:125], v[134:137], v[184:187], v[122:125]
	v_mfma_f32_16x16x32_bf16 v[122:125], v[138:141], v[190:193], v[122:125]
	v_mfma_f32_16x16x32_bf16 v[118:121], v[142:145], v[184:187], v[118:121]
	v_mfma_f32_16x16x32_bf16 v[118:121], v[146:149], v[190:193], v[118:121]
	v_mfma_f32_16x16x32_bf16 v[130:133], v[150:153], v[184:187], v[130:133]
	v_mfma_f32_16x16x32_bf16 v[130:133], v[154:157], v[190:193], v[130:133]
	v_mfma_f32_16x16x32_bf16 v[126:129], v[176:179], v[184:187], v[126:129]
	v_mfma_f32_16x16x32_bf16 v[126:129], v[180:183], v[190:193], v[126:129]
	v_mfma_f32_16x16x32_bf16 v[102:105], v[176:179], v[212:215], v[102:105]
	v_mfma_f32_16x16x32_bf16 v[102:105], v[180:183], v[216:219], v[102:105]
	v_mfma_f32_16x16x32_bf16 v[106:109], v[150:153], v[212:215], v[106:109]
	v_mfma_f32_16x16x32_bf16 v[106:109], v[154:157], v[216:219], v[106:109]
	v_mfma_f32_16x16x32_bf16 v[110:113], v[142:145], v[212:215], v[110:113]
	v_mfma_f32_16x16x32_bf16 v[110:113], v[146:149], v[216:219], v[110:113]
	v_mfma_f32_16x16x32_bf16 v[114:117], v[134:137], v[212:215], v[114:117]
	v_mfma_f32_16x16x32_bf16 v[114:117], v[138:141], v[216:219], v[114:117]
	v_mfma_f32_16x16x32_bf16 v[98:101], v[134:137], v[220:223], v[98:101]
	v_mfma_f32_16x16x32_bf16 v[98:101], v[138:141], v[224:227], v[98:101]
	v_mfma_f32_16x16x32_bf16 v[94:97], v[142:145], v[220:223], v[94:97]
	v_mfma_f32_16x16x32_bf16 v[94:97], v[146:149], v[224:227], v[94:97]
	v_mfma_f32_16x16x32_bf16 v[90:93], v[150:153], v[220:223], v[90:93]
	v_mfma_f32_16x16x32_bf16 v[90:93], v[154:157], v[224:227], v[90:93]
	v_mfma_f32_16x16x32_bf16 v[86:89], v[176:179], v[220:223], v[86:89]
	v_mfma_f32_16x16x32_bf16 v[86:89], v[180:183], v[224:227], v[86:89]
	v_mfma_f32_16x16x32_bf16 v[70:73], v[176:179], v[228:231], v[70:73]
	v_mfma_f32_16x16x32_bf16 v[70:73], v[180:183], v[232:235], v[70:73]
	v_mfma_f32_16x16x32_bf16 v[74:77], v[150:153], v[228:231], v[74:77]
	v_mfma_f32_16x16x32_bf16 v[74:77], v[154:157], v[232:235], v[74:77]
	v_mfma_f32_16x16x32_bf16 v[78:81], v[142:145], v[228:231], v[78:81]
	v_mfma_f32_16x16x32_bf16 v[78:81], v[146:149], v[232:235], v[78:81]
	v_mfma_f32_16x16x32_bf16 v[82:85], v[134:137], v[228:231], v[82:85]
	v_mfma_f32_16x16x32_bf16 v[82:85], v[138:141], v[232:235], v[82:85]
	s_barrier
	s_add_i32 s4, s24, 0x18000
	s_add_i32 m0, s4, 0xffffff80
	ds_read_b128 v[184:187], v188 offset:49152
	ds_read_b128 v[190:193], v188 offset:50176
	ds_read_b128 v[212:215], v188 offset:51200
	ds_read_b128 v[216:219], v188 offset:52224
	global_load_lds_dwordx4 v4, s[52:53] offset:128
	s_add_i32 m0, s4, 0x1f80
	s_add_u32 s22, s52, 0x160080
	s_addc_u32 s23, s53, 0
	s_add_i32 s4, s5, s24
	global_load_lds_dwordx4 v170, s[52:53] offset:128
	s_mov_b32 m0, s4
	ds_read_b128 v[220:223], v188 offset:53248
	global_load_lds_dwordx4 v4, s[22:23]
	s_add_i32 m0, s4, 0x2000
	ds_read_b128 v[224:227], v188 offset:54272
	global_load_lds_dwordx4 v170, s[22:23]
	s_add_i32 m0, s61, 0xffffff80
	ds_read_b128 v[228:231], v188 offset:55296
	global_load_lds_dwordx4 v2, s[54:55] offset:128
	s_add_i32 m0, s64, 0xffffff80
	ds_read_b128 v[232:235], v188 offset:56320
	global_load_lds_dwordx4 v168, s[54:55] offset:128
	s_waitcnt vmcnt(8)
	s_waitcnt lgkmcnt(0)
	s_barrier
	v_mfma_f32_16x16x32_bf16 v[58:61], v[134:137], v[184:187], v[58:61]
	v_mfma_f32_16x16x32_bf16 v[58:61], v[138:141], v[190:193], v[58:61]
	v_mfma_f32_16x16x32_bf16 v[54:57], v[142:145], v[184:187], v[54:57]
	v_mfma_f32_16x16x32_bf16 v[54:57], v[146:149], v[190:193], v[54:57]
	v_mfma_f32_16x16x32_bf16 v[66:69], v[150:153], v[184:187], v[66:69]
	v_mfma_f32_16x16x32_bf16 v[66:69], v[154:157], v[190:193], v[66:69]
	v_mfma_f32_16x16x32_bf16 v[62:65], v[176:179], v[184:187], v[62:65]
	v_mfma_f32_16x16x32_bf16 v[62:65], v[180:183], v[190:193], v[62:65]
	v_mfma_f32_16x16x32_bf16 v[38:41], v[176:179], v[212:215], v[38:41]
	v_mfma_f32_16x16x32_bf16 v[38:41], v[180:183], v[216:219], v[38:41]
	v_mfma_f32_16x16x32_bf16 v[42:45], v[150:153], v[212:215], v[42:45]
	v_mfma_f32_16x16x32_bf16 v[42:45], v[154:157], v[216:219], v[42:45]
	v_mfma_f32_16x16x32_bf16 v[46:49], v[142:145], v[212:215], v[46:49]
	v_mfma_f32_16x16x32_bf16 v[46:49], v[146:149], v[216:219], v[46:49]
	v_mfma_f32_16x16x32_bf16 v[50:53], v[134:137], v[212:215], v[50:53]
	v_mfma_f32_16x16x32_bf16 v[50:53], v[138:141], v[216:219], v[50:53]
	v_mfma_f32_16x16x32_bf16 v[34:37], v[134:137], v[220:223], v[34:37]
	v_mfma_f32_16x16x32_bf16 v[34:37], v[138:141], v[224:227], v[34:37]
	v_mfma_f32_16x16x32_bf16 v[30:33], v[142:145], v[220:223], v[30:33]
	v_mfma_f32_16x16x32_bf16 v[30:33], v[146:149], v[224:227], v[30:33]
	v_mfma_f32_16x16x32_bf16 v[26:29], v[150:153], v[220:223], v[26:29]
	v_mfma_f32_16x16x32_bf16 v[26:29], v[154:157], v[224:227], v[26:29]
	v_mfma_f32_16x16x32_bf16 v[22:25], v[176:179], v[220:223], v[22:25]
	v_mfma_f32_16x16x32_bf16 v[22:25], v[180:183], v[224:227], v[22:25]
	v_mfma_f32_16x16x32_bf16 v[6:9], v[176:179], v[228:231], v[6:9]
	v_mfma_f32_16x16x32_bf16 v[6:9], v[180:183], v[232:235], v[6:9]
	v_mfma_f32_16x16x32_bf16 v[10:13], v[150:153], v[228:231], v[10:13]
	v_mfma_f32_16x16x32_bf16 v[10:13], v[154:157], v[232:235], v[10:13]
	v_mfma_f32_16x16x32_bf16 v[14:17], v[142:145], v[228:231], v[14:17]
	v_mfma_f32_16x16x32_bf16 v[14:17], v[146:149], v[232:235], v[14:17]
	v_mfma_f32_16x16x32_bf16 v[18:21], v[134:137], v[228:231], v[18:21]
	v_mfma_f32_16x16x32_bf16 v[18:21], v[138:141], v[232:235], v[18:21]
	s_barrier
	s_add_i32 s20, s20, 2
	s_add_u32 s33, s33, 0x100
	s_addc_u32 s69, s69, 0
	s_cmpk_gt_u32 s20, 0x55
	s_mov_b64 s[22:23], s[50:51]
	s_cbranch_scc0 .LBB0_299
	s_and_b64 vcc, exec, s[46:47]
	s_cbranch_vccz .LBB0_302
	s_barrier

; #define PG8_STAGE(bufoff, gbase, voff) do { _Pragma("unroll") for (int _i = 0; _i < 2; ++_i) \
;         __builtin_amdgcn_global_load_lds((const unsigned*)((const char*)(gbase) + (voff)[_i]), (PG8_LAS unsigned*)(lds + (bufoff) + ldsw + _i * 8192), 16, 0, 0); } while (0)
; #define PG8_LDA(dst, b, h) do { _Pragma("unroll") for (int m = 0; m < 4; ++m) _Pragma("unroll") for (int k = 0; k < 2; ++k) dst[m][k] = *(const PG8_LAS bf16x8*)(lds + PG8_SA(b, h) + aoff + m * 2048 + k * 1024); } while (0)
; #define PG8_LDB(dst, b, h) do { _Pragma("unroll") for (int n = 0; n < 2; ++n) _Pragma("unroll") for (int k = 0; k < 2; ++k) dst[n][k] = *(const PG8_LAS bf16x8*)(lds + PG8_SB(b, h) + boff + n * 2048 + k * 1024); } while (0)
; #define PG8_MMA(ai, bj, At, Bt) do { __builtin_amdgcn_s_setprio(1); _Pragma("unroll") for (int m = 0; m < 4; ++m) _Pragma("unroll") for (int n = 0; n < 2; ++n) _Pragma("unroll") for (int k = 0; k < 2; ++k) \
;         acc[ai][bj][m][n] = __builtin_amdgcn_mfma_f32_16x16x32_bf16(Bt[n][k], At[m][k], acc[ai][bj][m][n], 0, 0, 0); __builtin_amdgcn_s_setprio(0); } while (0)
; #define PG8_WAIT_V(n) asm volatile("s_waitcnt vmcnt(" #n ")" ::: "memory")
; #define PG8_WAIT_L(n) asm volatile("s_waitcnt lgkmcnt(" #n ")" ::: "memory")
; #define PG8_BAR __builtin_amdgcn_s_barrier()
; #define PG8_SCHED __builtin_amdgcn_sched_barrier(0)
; template <class Epi, class Sched, bool ALIGN_EPI = false, bool SP2 = false>
; __device__ __forceinline__ void gemm_phase(PG8_LAS unsigned char* lds, const Gemm g, const Sched& S, const Epi& E) {
;     ...
;             PG8_LDB(B0, 0, 0); PG8_LDB(B1, 0, 1); PG8_SCHED; PG8_LDA(At, 0, 0); PG8_STAGE(PG8_SA(1, 1), a1 + hstep, voffA);
;             PG8_WAIT_V(8); PG8_WAIT_L(0); PG8_BAR; PG8_MMA(0, 0, At, B0); PG8_MMA(0, 1, At, B1); PG8_BAR; PG8_SCHED;
;             PG8_LDA(At, 0, 1); PG8_STAGE(PG8_SB(0, 0), b2, voffB); PG8_STAGE(PG8_SB(0, 1), b2 + hstep, voffB); PG8_STAGE(PG8_SA(0, 0), a2, voffA);
;             PG8_WAIT_V(8); PG8_WAIT_L(0); PG8_BAR; PG8_MMA(1, 0, At, B0); PG8_MMA(1, 1, At, B1); PG8_BAR; PG8_SCHED;
.LBB0_387:
	ds_read_b128 v[144:147], v156
	ds_read_b128 v[148:151], v156 offset:1024
	ds_read_b128 v[168:171], v156 offset:2048
	ds_read_b128 v[172:175], v156 offset:3072
	ds_read_b128 v[176:179], v157
	ds_read_b128 v[180:183], v157 offset:1024
	ds_read_b128 v[184:187], v157 offset:2048
	ds_read_b128 v[188:191], v157 offset:3072
	ds_read_b128 v[212:215], v155
	ds_read_b128 v[216:219], v155 offset:1024
	ds_read_b128 v[220:223], v155 offset:2048
	ds_read_b128 v[224:227], v155 offset:3072
	ds_read_b128 v[228:231], v155 offset:4096
	ds_read_b128 v[232:235], v155 offset:5120
	ds_read_b128 v[236:239], v155 offset:6144
	ds_read_b128 v[240:243], v155 offset:7168
	s_add_i32 m0, s60, 0xc000
	s_add_u32 s4, s56, 0xfff80080
	s_addc_u32 s5, s57, -1
	global_load_lds_dwordx4 v140, s[56:57]
	s_add_i32 m0, s60, 0xe000
	s_add_i32 s6, 0, 0x10000
	global_load_lds_dwordx4 v142, s[56:57]
	s_cmp_eq_u32 s20, 28
	s_cselect_b32 s59, s47, s5
	s_cselect_b32 s58, s75, s4
	s_cselect_b32 s55, s49, s77
	s_cselect_b32 s54, vcc_lo, s71
	s_waitcnt vmcnt(8)
	s_waitcnt lgkmcnt(0)
	s_barrier
	v_mfma_f32_16x16x32_bf16 v[122:125], v[144:147], v[212:215], v[122:125]
	v_mfma_f32_16x16x32_bf16 v[122:125], v[148:151], v[216:219], v[122:125]
	v_mfma_f32_16x16x32_bf16 v[118:121], v[168:171], v[212:215], v[118:121]
	v_mfma_f32_16x16x32_bf16 v[118:121], v[172:175], v[216:219], v[118:121]
	v_mfma_f32_16x16x32_bf16 v[130:133], v[176:179], v[212:215], v[130:133]
	v_mfma_f32_16x16x32_bf16 v[130:133], v[180:183], v[216:219], v[130:133]
	v_mfma_f32_16x16x32_bf16 v[126:129], v[184:187], v[212:215], v[126:129]
	v_mfma_f32_16x16x32_bf16 v[126:129], v[188:191], v[216:219], v[126:129]
	v_mfma_f32_16x16x32_bf16 v[110:113], v[184:187], v[220:223], v[110:113]
	v_mfma_f32_16x16x32_bf16 v[110:113], v[188:191], v[224:227], v[110:113]
	v_mfma_f32_16x16x32_bf16 v[114:117], v[176:179], v[220:223], v[114:117]
	v_mfma_f32_16x16x32_bf16 v[114:117], v[180:183], v[224:227], v[114:117]
	v_mfma_f32_16x16x32_bf16 v[102:105], v[168:171], v[220:223], v[102:105]
	v_mfma_f32_16x16x32_bf16 v[102:105], v[172:175], v[224:227], v[102:105]
	v_mfma_f32_16x16x32_bf16 v[106:109], v[144:147], v[220:223], v[106:109]
	v_mfma_f32_16x16x32_bf16 v[106:109], v[148:151], v[224:227], v[106:109]
	v_mfma_f32_16x16x32_bf16 v[90:93], v[144:147], v[228:231], v[90:93]
	v_mfma_f32_16x16x32_bf16 v[90:93], v[148:151], v[232:235], v[90:93]
	v_mfma_f32_16x16x32_bf16 v[86:89], v[168:171], v[228:231], v[86:89]
	v_mfma_f32_16x16x32_bf16 v[86:89], v[172:175], v[232:235], v[86:89]
	v_mfma_f32_16x16x32_bf16 v[98:101], v[176:179], v[228:231], v[98:101]
	v_mfma_f32_16x16x32_bf16 v[98:101], v[180:183], v[232:235], v[98:101]
	v_mfma_f32_16x16x32_bf16 v[94:97], v[184:187], v[228:231], v[94:97]
	v_mfma_f32_16x16x32_bf16 v[94:97], v[188:191], v[232:235], v[94:97]
	v_mfma_f32_16x16x32_bf16 v[78:81], v[184:187], v[236:239], v[78:81]
	v_mfma_f32_16x16x32_bf16 v[78:81], v[188:191], v[240:243], v[78:81]
	v_mfma_f32_16x16x32_bf16 v[82:85], v[176:179], v[236:239], v[82:85]
	v_mfma_f32_16x16x32_bf16 v[82:85], v[180:183], v[240:243], v[82:85]
	v_mfma_f32_16x16x32_bf16 v[70:73], v[168:171], v[236:239], v[70:73]
	v_mfma_f32_16x16x32_bf16 v[70:73], v[172:175], v[240:243], v[70:73]
	v_mfma_f32_16x16x32_bf16 v[74:77], v[144:147], v[236:239], v[74:77]
	v_mfma_f32_16x16x32_bf16 v[74:77], v[148:151], v[240:243], v[74:77]
	s_barrier
	ds_read_b128 v[212:215], v155 offset:16384
	ds_read_b128 v[216:219], v155 offset:17408
	ds_read_b128 v[220:223], v155 offset:18432
	ds_read_b128 v[224:227], v155 offset:19456
	s_add_i32 s5, s6, s24
	s_mov_b32 m0, s5
	s_add_u32 s34, s54, 0x80000
	s_addc_u32 s35, s55, 0
	global_load_lds_dwordx4 v4, s[54:55]
	s_add_i32 m0, s5, 0x2000
	s_add_i32 s4, s24, 0x14000
	global_load_lds_dwordx4 v2, s[54:55]
	s_mov_b32 m0, s4
	ds_read_b128 v[228:231], v155 offset:20480
	global_load_lds_dwordx4 v4, s[34:35]
	s_add_i32 m0, s4, 0x2000
	ds_read_b128 v[232:235], v155 offset:21504
	global_load_lds_dwordx4 v2, s[34:35]
	s_mov_b32 m0, s60
	ds_read_b128 v[236:239], v155 offset:22528
	global_load_lds_dwordx4 v136, s[58:59]
	s_mov_b32 m0, s61
	ds_read_b128 v[240:243], v155 offset:23552
	global_load_lds_dwordx4 v134, s[58:59]
	s_waitcnt vmcnt(8)
	s_waitcnt lgkmcnt(0)
	s_barrier
	v_mfma_f32_16x16x32_bf16 v[58:61], v[144:147], v[212:215], v[58:61]
	v_mfma_f32_16x16x32_bf16 v[58:61], v[148:151], v[216:219], v[58:61]
	v_mfma_f32_16x16x32_bf16 v[54:57], v[168:171], v[212:215], v[54:57]
	v_mfma_f32_16x16x32_bf16 v[54:57], v[172:175], v[216:219], v[54:57]
	v_mfma_f32_16x16x32_bf16 v[66:69], v[176:179], v[212:215], v[66:69]
	v_mfma_f32_16x16x32_bf16 v[66:69], v[180:183], v[216:219], v[66:69]
	v_mfma_f32_16x16x32_bf16 v[62:65], v[184:187], v[212:215], v[62:65]
	v_mfma_f32_16x16x32_bf16 v[62:65], v[188:191], v[216:219], v[62:65]
	v_mfma_f32_16x16x32_bf16 v[46:49], v[184:187], v[220:223], v[46:49]
	v_mfma_f32_16x16x32_bf16 v[46:49], v[188:191], v[224:227], v[46:49]
	v_mfma_f32_16x16x32_bf16 v[50:53], v[176:179], v[220:223], v[50:53]
	v_mfma_f32_16x16x32_bf16 v[50:53], v[180:183], v[224:227], v[50:53]
	v_mfma_f32_16x16x32_bf16 v[38:41], v[168:171], v[220:223], v[38:41]
	v_mfma_f32_16x16x32_bf16 v[38:41], v[172:175], v[224:227], v[38:41]
	v_mfma_f32_16x16x32_bf16 v[42:45], v[144:147], v[220:223], v[42:45]
	v_mfma_f32_16x16x32_bf16 v[42:45], v[148:151], v[224:227], v[42:45]
	v_mfma_f32_16x16x32_bf16 v[26:29], v[144:147], v[228:231], v[26:29]
	v_mfma_f32_16x16x32_bf16 v[26:29], v[148:151], v[232:235], v[26:29]
	v_mfma_f32_16x16x32_bf16 v[22:25], v[168:171], v[228:231], v[22:25]
	v_mfma_f32_16x16x32_bf16 v[22:25], v[172:175], v[232:235], v[22:25]
	v_mfma_f32_16x16x32_bf16 v[34:37], v[176:179], v[228:231], v[34:37]
	v_mfma_f32_16x16x32_bf16 v[34:37], v[180:183], v[232:235], v[34:37]
	v_mfma_f32_16x16x32_bf16 v[30:33], v[184:187], v[228:231], v[30:33]
	v_mfma_f32_16x16x32_bf16 v[30:33], v[188:191], v[232:235], v[30:33]
	v_mfma_f32_16x16x32_bf16 v[18:21], v[184:187], v[236:239], v[18:21]
	v_mfma_f32_16x16x32_bf16 v[18:21], v[188:191], v[240:243], v[18:21]
	v_mfma_f32_16x16x32_bf16 v[14:17], v[176:179], v[236:239], v[14:17]
	v_mfma_f32_16x16x32_bf16 v[14:17], v[180:183], v[240:243], v[14:17]
	v_mfma_f32_16x16x32_bf16 v[6:9], v[168:171], v[236:239], v[6:9]
	v_mfma_f32_16x16x32_bf16 v[6:9], v[172:175], v[240:243], v[6:9]
	v_mfma_f32_16x16x32_bf16 v[10:13], v[144:147], v[236:239], v[10:13]
	v_mfma_f32_16x16x32_bf16 v[10:13], v[148:151], v[240:243], v[10:13]
	s_barrier
; #define PG8_STAGE(bufoff, gbase, voff) do { _Pragma("unroll") for (int _i = 0; _i < 2; ++_i) \
;         __builtin_amdgcn_global_load_lds((const unsigned*)((const char*)(gbase) + (voff)[_i]), (PG8_LAS unsigned*)(lds + (bufoff) + ldsw + _i * 8192), 16, 0, 0); } while (0)
; #define PG8_LDA(dst, b, h) do { _Pragma("unroll") for (int m = 0; m < 4; ++m) _Pragma("unroll") for (int k = 0; k < 2; ++k) dst[m][k] = *(const PG8_LAS bf16x8*)(lds + PG8_SA(b, h) + aoff + m * 2048 + k * 1024); } while (0)
; #define PG8_LDB(dst, b, h) do { _Pragma("unroll") for (int n = 0; n < 2; ++n) _Pragma("unroll") for (int k = 0; k < 2; ++k) dst[n][k] = *(const PG8_LAS bf16x8*)(lds + PG8_SB(b, h) + boff + n * 2048 + k * 1024); } while (0)
; #define PG8_MMA(ai, bj, At, Bt) do { __builtin_amdgcn_s_setprio(1); _Pragma("unroll") for (int m = 0; m < 4; ++m) _Pragma("unroll") for (int n = 0; n < 2; ++n) _Pragma("unroll") for (int k = 0; k < 2; ++k) \
;         acc[ai][bj][m][n] = __builtin_amdgcn_mfma_f32_16x16x32_bf16(Bt[n][k], At[m][k], acc[ai][bj][m][n], 0, 0, 0); __builtin_amdgcn_s_setprio(0); } while (0)
; #define PG8_WAIT_V(n) asm volatile("s_waitcnt vmcnt(" #n ")" ::: "memory")
; #define PG8_WAIT_L(n) asm volatile("s_waitcnt lgkmcnt(" #n ")" ::: "memory")
; #define PG8_BAR __builtin_amdgcn_s_barrier()
; #define PG8_SCHED __builtin_amdgcn_sched_barrier(0)
; template <class Epi, class Sched, bool ALIGN_EPI = false, bool SP2 = false>
; __device__ __forceinline__ void gemm_phase(PG8_LAS unsigned char* lds, const Gemm g, const Sched& S, const Epi& E) {
;     ...
;             PG8_LDB(B0, 1, 0); PG8_LDB(B1, 1, 1); PG8_SCHED; PG8_LDA(At, 1, 0); PG8_STAGE(PG8_SA(0, 1), a2 + hstep, voffA);
;             PG8_WAIT_V(8); PG8_WAIT_L(0); PG8_BAR; PG8_MMA(0, 0, At, B0); PG8_MMA(0, 1, At, B1); PG8_BAR; PG8_SCHED;
;             PG8_LDA(At, 1, 1); PG8_STAGE(PG8_SB(1, 0), b3, voffB); PG8_STAGE(PG8_SB(1, 1), b3 + hstep, voffB); PG8_STAGE(PG8_SA(1, 0), a3, voffA);
;             PG8_WAIT_V(8); PG8_WAIT_L(0); PG8_BAR; PG8_MMA(1, 0, At, B0); PG8_MMA(1, 1, At, B1); PG8_BAR; PG8_SCHED;
	ds_read_b128 v[144:147], v192
	ds_read_b128 v[148:151], v192 offset:1024
	ds_read_b128 v[168:171], v192 offset:2048
	ds_read_b128 v[172:175], v192 offset:3072
	ds_read_b128 v[176:179], v193
	ds_read_b128 v[180:183], v193 offset:1024
	ds_read_b128 v[184:187], v193 offset:2048
	ds_read_b128 v[188:191], v193 offset:3072
	ds_read_b128 v[212:215], v155 offset:32768
	ds_read_b128 v[216:219], v155 offset:33792
	ds_read_b128 v[220:223], v155 offset:34816
	ds_read_b128 v[224:227], v155 offset:35840
	ds_read_b128 v[228:231], v155 offset:36864
	ds_read_b128 v[232:235], v155 offset:37888
	ds_read_b128 v[236:239], v155 offset:38912
	ds_read_b128 v[240:243], v155 offset:39936
	s_add_u32 s34, s58, 0x80000
	s_addc_u32 s35, s59, 0
	s_mov_b32 m0, s64
	global_load_lds_dwordx4 v136, s[34:35]
	s_mov_b32 m0, s65
	s_add_i32 s5, 0, 0x1c000
	global_load_lds_dwordx4 v134, s[34:35]
	s_waitcnt vmcnt(8)
	s_waitcnt lgkmcnt(0)
	s_barrier
	v_mfma_f32_16x16x32_bf16 v[122:125], v[144:147], v[212:215], v[122:125]
	v_mfma_f32_16x16x32_bf16 v[122:125], v[148:151], v[216:219], v[122:125]
	v_mfma_f32_16x16x32_bf16 v[118:121], v[168:171], v[212:215], v[118:121]
	v_mfma_f32_16x16x32_bf16 v[118:121], v[172:175], v[216:219], v[118:121]
	v_mfma_f32_16x16x32_bf16 v[130:133], v[176:179], v[212:215], v[130:133]
	v_mfma_f32_16x16x32_bf16 v[130:133], v[180:183], v[216:219], v[130:133]
	v_mfma_f32_16x16x32_bf16 v[126:129], v[184:187], v[212:215], v[126:129]
	v_mfma_f32_16x16x32_bf16 v[126:129], v[188:191], v[216:219], v[126:129]
	v_mfma_f32_16x16x32_bf16 v[110:113], v[184:187], v[220:223], v[110:113]
	v_mfma_f32_16x16x32_bf16 v[110:113], v[188:191], v[224:227], v[110:113]
	v_mfma_f32_16x16x32_bf16 v[114:117], v[176:179], v[220:223], v[114:117]
	v_mfma_f32_16x16x32_bf16 v[114:117], v[180:183], v[224:227], v[114:117]
	v_mfma_f32_16x16x32_bf16 v[102:105], v[168:171], v[220:223], v[102:105]
	v_mfma_f32_16x16x32_bf16 v[102:105], v[172:175], v[224:227], v[102:105]
	v_mfma_f32_16x16x32_bf16 v[106:109], v[144:147], v[220:223], v[106:109]
	v_mfma_f32_16x16x32_bf16 v[106:109], v[148:151], v[224:227], v[106:109]
	v_mfma_f32_16x16x32_bf16 v[90:93], v[144:147], v[228:231], v[90:93]
	v_mfma_f32_16x16x32_bf16 v[90:93], v[148:151], v[232:235], v[90:93]
	v_mfma_f32_16x16x32_bf16 v[86:89], v[168:171], v[228:231], v[86:89]
	v_mfma_f32_16x16x32_bf16 v[86:89], v[172:175], v[232:235], v[86:89]
	v_mfma_f32_16x16x32_bf16 v[98:101], v[176:179], v[228:231], v[98:101]
	v_mfma_f32_16x16x32_bf16 v[98:101], v[180:183], v[232:235], v[98:101]
	v_mfma_f32_16x16x32_bf16 v[94:97], v[184:187], v[228:231], v[94:97]
	v_mfma_f32_16x16x32_bf16 v[94:97], v[188:191], v[232:235], v[94:97]
	v_mfma_f32_16x16x32_bf16 v[78:81], v[184:187], v[236:239], v[78:81]
	v_mfma_f32_16x16x32_bf16 v[78:81], v[188:191], v[240:243], v[78:81]
	v_mfma_f32_16x16x32_bf16 v[82:85], v[176:179], v[236:239], v[82:85]
	v_mfma_f32_16x16x32_bf16 v[82:85], v[180:183], v[240:243], v[82:85]
	v_mfma_f32_16x16x32_bf16 v[70:73], v[168:171], v[236:239], v[70:73]
	v_mfma_f32_16x16x32_bf16 v[70:73], v[172:175], v[240:243], v[70:73]
	v_mfma_f32_16x16x32_bf16 v[74:77], v[144:147], v[236:239], v[74:77]
	v_mfma_f32_16x16x32_bf16 v[74:77], v[148:151], v[240:243], v[74:77]
	s_barrier
	ds_read_b128 v[212:215], v155 offset:49152
	ds_read_b128 v[216:219], v155 offset:50176
	ds_read_b128 v[220:223], v155 offset:51200
	s_add_i32 s4, s24, 0x18000
	s_add_i32 m0, s4, 0xffffff80
	ds_read_b128 v[224:227], v155 offset:52224
	global_load_lds_dwordx4 v4, s[54:55] offset:128
	s_add_i32 m0, s4, 0x1f80
	s_add_i32 s4, s5, s24
	global_load_lds_dwordx4 v2, s[54:55] offset:128
	s_add_u32 s34, s54, 0x80080
	s_addc_u32 s35, s55, 0
	s_mov_b32 m0, s4
	ds_read_b128 v[228:231], v155 offset:53248
	global_load_lds_dwordx4 v4, s[34:35]
	s_add_i32 m0, s4, 0x2000
	ds_read_b128 v[232:235], v155 offset:54272
	global_load_lds_dwordx4 v2, s[34:35]
	s_add_i32 m0, s67, 0xffffff80
	ds_read_b128 v[236:239], v155 offset:55296
	global_load_lds_dwordx4 v136, s[58:59] offset:128
	s_add_i32 m0, s72, 0xffffff80
	ds_read_b128 v[240:243], v155 offset:56320
	global_load_lds_dwordx4 v134, s[58:59] offset:128
	s_waitcnt vmcnt(8)
	s_waitcnt lgkmcnt(0)
	s_barrier
	v_mfma_f32_16x16x32_bf16 v[58:61], v[144:147], v[212:215], v[58:61]
	v_mfma_f32_16x16x32_bf16 v[58:61], v[148:151], v[216:219], v[58:61]
	v_mfma_f32_16x16x32_bf16 v[54:57], v[168:171], v[212:215], v[54:57]
	v_mfma_f32_16x16x32_bf16 v[54:57], v[172:175], v[216:219], v[54:57]
	v_mfma_f32_16x16x32_bf16 v[66:69], v[176:179], v[212:215], v[66:69]
	v_mfma_f32_16x16x32_bf16 v[66:69], v[180:183], v[216:219], v[66:69]
	v_mfma_f32_16x16x32_bf16 v[62:65], v[184:187], v[212:215], v[62:65]
	v_mfma_f32_16x16x32_bf16 v[62:65], v[188:191], v[216:219], v[62:65]
	v_mfma_f32_16x16x32_bf16 v[46:49], v[184:187], v[220:223], v[46:49]
	v_mfma_f32_16x16x32_bf16 v[46:49], v[188:191], v[224:227], v[46:49]
	v_mfma_f32_16x16x32_bf16 v[50:53], v[176:179], v[220:223], v[50:53]
	v_mfma_f32_16x16x32_bf16 v[50:53], v[180:183], v[224:227], v[50:53]
	v_mfma_f32_16x16x32_bf16 v[38:41], v[168:171], v[220:223], v[38:41]
	v_mfma_f32_16x16x32_bf16 v[38:41], v[172:175], v[224:227], v[38:41]
	v_mfma_f32_16x16x32_bf16 v[42:45], v[144:147], v[220:223], v[42:45]
	v_mfma_f32_16x16x32_bf16 v[42:45], v[148:151], v[224:227], v[42:45]
	v_mfma_f32_16x16x32_bf16 v[26:29], v[144:147], v[228:231], v[26:29]
	v_mfma_f32_16x16x32_bf16 v[26:29], v[148:151], v[232:235], v[26:29]
	v_mfma_f32_16x16x32_bf16 v[22:25], v[168:171], v[228:231], v[22:25]
	v_mfma_f32_16x16x32_bf16 v[22:25], v[172:175], v[232:235], v[22:25]
	v_mfma_f32_16x16x32_bf16 v[34:37], v[176:179], v[228:231], v[34:37]
	v_mfma_f32_16x16x32_bf16 v[34:37], v[180:183], v[232:235], v[34:37]
	v_mfma_f32_16x16x32_bf16 v[30:33], v[184:187], v[228:231], v[30:33]
	v_mfma_f32_16x16x32_bf16 v[30:33], v[188:191], v[232:235], v[30:33]
	v_mfma_f32_16x16x32_bf16 v[18:21], v[184:187], v[236:239], v[18:21]
	v_mfma_f32_16x16x32_bf16 v[18:21], v[188:191], v[240:243], v[18:21]
	v_mfma_f32_16x16x32_bf16 v[14:17], v[176:179], v[236:239], v[14:17]
	v_mfma_f32_16x16x32_bf16 v[14:17], v[180:183], v[240:243], v[14:17]
	v_mfma_f32_16x16x32_bf16 v[6:9], v[168:171], v[236:239], v[6:9]
	v_mfma_f32_16x16x32_bf16 v[6:9], v[172:175], v[240:243], v[6:9]
	v_mfma_f32_16x16x32_bf16 v[10:13], v[144:147], v[236:239], v[10:13]
	v_mfma_f32_16x16x32_bf16 v[10:13], v[148:151], v[240:243], v[10:13]
	s_barrier
	s_add_i32 s20, s20, 2
	s_add_u32 s56, s56, 0x100
	s_addc_u32 s57, s57, 0
	s_add_u32 s71, s71, 0x100
	s_addc_u32 s77, s77, 0
	s_cmp_gt_u32 s20, 29
	s_cbranch_scc0 .LBB0_387
	s_and_b64 vcc, exec, s[44:45]
	s_movk_i32 s75, 0x800
	s_movk_i32 s77, 0x6000
	s_mov_b32 s71, 0x44800000
	s_cbranch_vccz .LBB0_390
	s_barrier

; #define PG8_STAGE(bufoff, gbase, voff) do { _Pragma("unroll") for (int _i = 0; _i < 2; ++_i) \
;         __builtin_amdgcn_global_load_lds((const unsigned*)((const char*)(gbase) + (voff)[_i]), (PG8_LAS unsigned*)(lds + (bufoff) + ldsw + _i * 8192), 16, 0, 0); } while (0)
; #define PG8_LDA(dst, b, h) do { _Pragma("unroll") for (int m = 0; m < 4; ++m) _Pragma("unroll") for (int k = 0; k < 2; ++k) dst[m][k] = *(const PG8_LAS bf16x8*)(lds + PG8_SA(b, h) + aoff + m * 2048 + k * 1024); } while (0)
; #define PG8_LDB(dst, b, h) do { _Pragma("unroll") for (int n = 0; n < 2; ++n) _Pragma("unroll") for (int k = 0; k < 2; ++k) dst[n][k] = *(const PG8_LAS bf16x8*)(lds + PG8_SB(b, h) + boff + n * 2048 + k * 1024); } while (0)
; #define PG8_MMA(ai, bj, At, Bt) do { __builtin_amdgcn_s_setprio(1); _Pragma("unroll") for (int m = 0; m < 4; ++m) _Pragma("unroll") for (int n = 0; n < 2; ++n) _Pragma("unroll") for (int k = 0; k < 2; ++k) \
;         acc[ai][bj][m][n] = __builtin_amdgcn_mfma_f32_16x16x32_bf16(Bt[n][k], At[m][k], acc[ai][bj][m][n], 0, 0, 0); __builtin_amdgcn_s_setprio(0); } while (0)
; #define PG8_WAIT_V(n) asm volatile("s_waitcnt vmcnt(" #n ")" ::: "memory")
; #define PG8_WAIT_L(n) asm volatile("s_waitcnt lgkmcnt(" #n ")" ::: "memory")
; #define PG8_BAR __builtin_amdgcn_s_barrier()
; #define PG8_SCHED __builtin_amdgcn_sched_barrier(0)
; template <class Epi, class Sched, bool ALIGN_EPI = false, bool SP2 = false>
; __device__ __forceinline__ void gemm_phase(PG8_LAS unsigned char* lds, const Gemm g, const Sched& S, const Epi& E) {
;     ...
;             PG8_LDB(B0, 0, 0); PG8_LDB(B1, 0, 1); PG8_SCHED; PG8_LDA(At, 0, 0); PG8_STAGE(PG8_SA(1, 1), a1 + hstep, voffA);
;             PG8_WAIT_V(8); PG8_WAIT_L(0); PG8_BAR; PG8_MMA(0, 0, At, B0); PG8_MMA(0, 1, At, B1); PG8_BAR; PG8_SCHED;
;             PG8_LDA(At, 0, 1); PG8_STAGE(PG8_SB(0, 0), b2, voffB); PG8_STAGE(PG8_SB(0, 1), b2 + hstep, voffB); PG8_STAGE(PG8_SA(0, 0), a2, voffA);
;             PG8_WAIT_V(8); PG8_WAIT_L(0); PG8_BAR; PG8_MMA(1, 0, At, B0); PG8_MMA(1, 1, At, B1); PG8_BAR; PG8_SCHED;
.LBB0_1738:
	s_add_u32 s4, s50, 0xfff80080
	s_addc_u32 s5, s51, -1
	s_add_i32 s6, 0, 0x10000
	s_cmp_eq_u32 s20, 28
	s_cselect_b32 s53, s43, s5
	s_cselect_b32 s52, s66, s4
	s_cselect_b32 s49, s45, s71
	s_cselect_b32 s48, s67, s69
	ds_read_b128 v[134:137], v234
	ds_read_b128 v[138:141], v234 offset:1024
	ds_read_b128 v[142:145], v234 offset:2048
	ds_read_b128 v[146:149], v234 offset:3072
	ds_read_b128 v[150:153], v235
	ds_read_b128 v[154:157], v235 offset:1024
	ds_read_b128 v[176:179], v235 offset:2048
	ds_read_b128 v[180:183], v235 offset:3072
	s_add_i32 m0, s54, 0xc000
	ds_read_b128 v[184:187], v188
	ds_read_b128 v[190:193], v188 offset:1024
	ds_read_b128 v[210:213], v188 offset:2048
	ds_read_b128 v[214:217], v188 offset:3072
	ds_read_b128 v[218:221], v188 offset:4096
	ds_read_b128 v[222:225], v188 offset:5120
	ds_read_b128 v[226:229], v188 offset:6144
	global_load_lds_dwordx4 v172, s[50:51]
	s_add_i32 m0, s54, 0xe000
	ds_read_b128 v[230:233], v188 offset:7168
	global_load_lds_dwordx4 v174, s[50:51]
	s_waitcnt vmcnt(8)
	s_waitcnt lgkmcnt(0)
	s_barrier
	v_mfma_f32_16x16x32_bf16 v[122:125], v[134:137], v[184:187], v[122:125]
	v_mfma_f32_16x16x32_bf16 v[122:125], v[138:141], v[190:193], v[122:125]
	v_mfma_f32_16x16x32_bf16 v[118:121], v[142:145], v[184:187], v[118:121]
	v_mfma_f32_16x16x32_bf16 v[118:121], v[146:149], v[190:193], v[118:121]
	v_mfma_f32_16x16x32_bf16 v[130:133], v[150:153], v[184:187], v[130:133]
	v_mfma_f32_16x16x32_bf16 v[130:133], v[154:157], v[190:193], v[130:133]
	v_mfma_f32_16x16x32_bf16 v[126:129], v[176:179], v[184:187], v[126:129]
	v_mfma_f32_16x16x32_bf16 v[126:129], v[180:183], v[190:193], v[126:129]
	v_mfma_f32_16x16x32_bf16 v[102:105], v[176:179], v[210:213], v[102:105]
	v_mfma_f32_16x16x32_bf16 v[102:105], v[180:183], v[214:217], v[102:105]
	v_mfma_f32_16x16x32_bf16 v[110:113], v[150:153], v[210:213], v[110:113]
	v_mfma_f32_16x16x32_bf16 v[110:113], v[154:157], v[214:217], v[110:113]
	v_mfma_f32_16x16x32_bf16 v[106:109], v[142:145], v[210:213], v[106:109]
	v_mfma_f32_16x16x32_bf16 v[106:109], v[146:149], v[214:217], v[106:109]
	v_mfma_f32_16x16x32_bf16 v[114:117], v[134:137], v[210:213], v[114:117]
	v_mfma_f32_16x16x32_bf16 v[114:117], v[138:141], v[214:217], v[114:117]
	v_mfma_f32_16x16x32_bf16 v[98:101], v[134:137], v[218:221], v[98:101]
	v_mfma_f32_16x16x32_bf16 v[98:101], v[138:141], v[222:225], v[98:101]
	v_mfma_f32_16x16x32_bf16 v[90:93], v[142:145], v[218:221], v[90:93]
	v_mfma_f32_16x16x32_bf16 v[90:93], v[146:149], v[222:225], v[90:93]
	v_mfma_f32_16x16x32_bf16 v[94:97], v[150:153], v[218:221], v[94:97]
	v_mfma_f32_16x16x32_bf16 v[94:97], v[154:157], v[222:225], v[94:97]
	v_mfma_f32_16x16x32_bf16 v[86:89], v[176:179], v[218:221], v[86:89]
	v_mfma_f32_16x16x32_bf16 v[86:89], v[180:183], v[222:225], v[86:89]
	v_mfma_f32_16x16x32_bf16 v[70:73], v[176:179], v[226:229], v[70:73]
	v_mfma_f32_16x16x32_bf16 v[70:73], v[180:183], v[230:233], v[70:73]
	v_mfma_f32_16x16x32_bf16 v[78:81], v[150:153], v[226:229], v[78:81]
	v_mfma_f32_16x16x32_bf16 v[78:81], v[154:157], v[230:233], v[78:81]
	v_mfma_f32_16x16x32_bf16 v[74:77], v[142:145], v[226:229], v[74:77]
	v_mfma_f32_16x16x32_bf16 v[74:77], v[146:149], v[230:233], v[74:77]
	v_mfma_f32_16x16x32_bf16 v[82:85], v[134:137], v[226:229], v[82:85]
	v_mfma_f32_16x16x32_bf16 v[82:85], v[138:141], v[230:233], v[82:85]
	s_barrier
	s_add_i32 s5, s6, s24
	s_mov_b32 m0, s5
	ds_read_b128 v[184:187], v188 offset:16384
	ds_read_b128 v[190:193], v188 offset:17408
	ds_read_b128 v[210:213], v188 offset:18432
	ds_read_b128 v[214:217], v188 offset:19456
	global_load_lds_dwordx4 v4, s[48:49]
	s_add_i32 m0, s5, 0x2000
	s_add_u32 s34, s48, 0x80000
	s_addc_u32 s35, s49, 0
	s_add_i32 s4, s24, 0x14000
	global_load_lds_dwordx4 v2, s[48:49]
	s_mov_b32 m0, s4
	ds_read_b128 v[218:221], v188 offset:20480
	global_load_lds_dwordx4 v4, s[34:35]
	s_add_i32 m0, s4, 0x2000
	ds_read_b128 v[222:225], v188 offset:21504
	global_load_lds_dwordx4 v2, s[34:35]
	s_mov_b32 m0, s54
	ds_read_b128 v[226:229], v188 offset:22528
	global_load_lds_dwordx4 v170, s[52:53]
	s_mov_b32 m0, s55
	ds_read_b128 v[230:233], v188 offset:23552
	global_load_lds_dwordx4 v168, s[52:53]
	s_waitcnt vmcnt(8)
	s_waitcnt lgkmcnt(0)
	s_barrier
	v_mfma_f32_16x16x32_bf16 v[58:61], v[134:137], v[184:187], v[58:61]
	v_mfma_f32_16x16x32_bf16 v[58:61], v[138:141], v[190:193], v[58:61]
	v_mfma_f32_16x16x32_bf16 v[54:57], v[142:145], v[184:187], v[54:57]
	v_mfma_f32_16x16x32_bf16 v[54:57], v[146:149], v[190:193], v[54:57]
	v_mfma_f32_16x16x32_bf16 v[66:69], v[150:153], v[184:187], v[66:69]
	v_mfma_f32_16x16x32_bf16 v[66:69], v[154:157], v[190:193], v[66:69]
	v_mfma_f32_16x16x32_bf16 v[62:65], v[176:179], v[184:187], v[62:65]
	v_mfma_f32_16x16x32_bf16 v[62:65], v[180:183], v[190:193], v[62:65]
	v_mfma_f32_16x16x32_bf16 v[38:41], v[176:179], v[210:213], v[38:41]
	v_mfma_f32_16x16x32_bf16 v[38:41], v[180:183], v[214:217], v[38:41]
	v_mfma_f32_16x16x32_bf16 v[46:49], v[150:153], v[210:213], v[46:49]
	v_mfma_f32_16x16x32_bf16 v[46:49], v[154:157], v[214:217], v[46:49]
	v_mfma_f32_16x16x32_bf16 v[42:45], v[142:145], v[210:213], v[42:45]
	v_mfma_f32_16x16x32_bf16 v[42:45], v[146:149], v[214:217], v[42:45]
	v_mfma_f32_16x16x32_bf16 v[50:53], v[134:137], v[210:213], v[50:53]
	v_mfma_f32_16x16x32_bf16 v[50:53], v[138:141], v[214:217], v[50:53]
	v_mfma_f32_16x16x32_bf16 v[34:37], v[134:137], v[218:221], v[34:37]
	v_mfma_f32_16x16x32_bf16 v[34:37], v[138:141], v[222:225], v[34:37]
	v_mfma_f32_16x16x32_bf16 v[26:29], v[142:145], v[218:221], v[26:29]
	v_mfma_f32_16x16x32_bf16 v[26:29], v[146:149], v[222:225], v[26:29]
	v_mfma_f32_16x16x32_bf16 v[30:33], v[150:153], v[218:221], v[30:33]
	v_mfma_f32_16x16x32_bf16 v[30:33], v[154:157], v[222:225], v[30:33]
	v_mfma_f32_16x16x32_bf16 v[22:25], v[176:179], v[218:221], v[22:25]
	v_mfma_f32_16x16x32_bf16 v[22:25], v[180:183], v[222:225], v[22:25]
	v_mfma_f32_16x16x32_bf16 v[6:9], v[176:179], v[226:229], v[6:9]
	v_mfma_f32_16x16x32_bf16 v[6:9], v[180:183], v[230:233], v[6:9]
	v_mfma_f32_16x16x32_bf16 v[14:17], v[150:153], v[226:229], v[14:17]
	v_mfma_f32_16x16x32_bf16 v[14:17], v[154:157], v[230:233], v[14:17]
	v_mfma_f32_16x16x32_bf16 v[10:13], v[142:145], v[226:229], v[10:13]
	v_mfma_f32_16x16x32_bf16 v[10:13], v[146:149], v[230:233], v[10:13]
	v_mfma_f32_16x16x32_bf16 v[18:21], v[134:137], v[226:229], v[18:21]
	v_mfma_f32_16x16x32_bf16 v[18:21], v[138:141], v[230:233], v[18:21]
	s_barrier
; #define PG8_STAGE(bufoff, gbase, voff) do { _Pragma("unroll") for (int _i = 0; _i < 2; ++_i) \
;         __builtin_amdgcn_global_load_lds((const unsigned*)((const char*)(gbase) + (voff)[_i]), (PG8_LAS unsigned*)(lds + (bufoff) + ldsw + _i * 8192), 16, 0, 0); } while (0)
; #define PG8_LDA(dst, b, h) do { _Pragma("unroll") for (int m = 0; m < 4; ++m) _Pragma("unroll") for (int k = 0; k < 2; ++k) dst[m][k] = *(const PG8_LAS bf16x8*)(lds + PG8_SA(b, h) + aoff + m * 2048 + k * 1024); } while (0)
; #define PG8_LDB(dst, b, h) do { _Pragma("unroll") for (int n = 0; n < 2; ++n) _Pragma("unroll") for (int k = 0; k < 2; ++k) dst[n][k] = *(const PG8_LAS bf16x8*)(lds + PG8_SB(b, h) + boff + n * 2048 + k * 1024); } while (0)
; #define PG8_MMA(ai, bj, At, Bt) do { __builtin_amdgcn_s_setprio(1); _Pragma("unroll") for (int m = 0; m < 4; ++m) _Pragma("unroll") for (int n = 0; n < 2; ++n) _Pragma("unroll") for (int k = 0; k < 2; ++k) \
;         acc[ai][bj][m][n] = __builtin_amdgcn_mfma_f32_16x16x32_bf16(Bt[n][k], At[m][k], acc[ai][bj][m][n], 0, 0, 0); __builtin_amdgcn_s_setprio(0); } while (0)
; #define PG8_WAIT_V(n) asm volatile("s_waitcnt vmcnt(" #n ")" ::: "memory")
; #define PG8_WAIT_L(n) asm volatile("s_waitcnt lgkmcnt(" #n ")" ::: "memory")
; #define PG8_BAR __builtin_amdgcn_s_barrier()
; #define PG8_SCHED __builtin_amdgcn_sched_barrier(0)
; template <class Epi, class Sched, bool ALIGN_EPI = false, bool SP2 = false>
; __device__ __forceinline__ void gemm_phase(PG8_LAS unsigned char* lds, const Gemm g, const Sched& S, const Epi& E) {
;     ...
;             PG8_LDB(B0, 1, 0); PG8_LDB(B1, 1, 1); PG8_SCHED; PG8_LDA(At, 1, 0); PG8_STAGE(PG8_SA(0, 1), a2 + hstep, voffA);
;             PG8_WAIT_V(8); PG8_WAIT_L(0); PG8_BAR; PG8_MMA(0, 0, At, B0); PG8_MMA(0, 1, At, B1); PG8_BAR; PG8_SCHED;
;             PG8_LDA(At, 1, 1); PG8_STAGE(PG8_SB(1, 0), b3, voffB); PG8_STAGE(PG8_SB(1, 1), b3 + hstep, voffB); PG8_STAGE(PG8_SA(1, 0), a3, voffA);
;             PG8_WAIT_V(8); PG8_WAIT_L(0); PG8_BAR; PG8_MMA(1, 0, At, B0); PG8_MMA(1, 1, At, B1); PG8_BAR; PG8_SCHED;
	s_add_i32 s5, 0, 0x1c000
	ds_read_b128 v[134:137], v236
	ds_read_b128 v[138:141], v236 offset:1024
	ds_read_b128 v[142:145], v236 offset:2048
	ds_read_b128 v[146:149], v236 offset:3072
	ds_read_b128 v[150:153], v237
	ds_read_b128 v[154:157], v237 offset:1024
	ds_read_b128 v[176:179], v237 offset:2048
	ds_read_b128 v[180:183], v237 offset:3072
	s_add_u32 s34, s52, 0x80000
	s_addc_u32 s35, s53, 0
	s_mov_b32 m0, s56
	ds_read_b128 v[184:187], v188 offset:32768
	ds_read_b128 v[190:193], v188 offset:33792
	ds_read_b128 v[210:213], v188 offset:34816
	ds_read_b128 v[214:217], v188 offset:35840
	ds_read_b128 v[218:221], v188 offset:36864
	ds_read_b128 v[222:225], v188 offset:37888
	ds_read_b128 v[226:229], v188 offset:38912
	global_load_lds_dwordx4 v170, s[34:35]
	s_mov_b32 m0, s57
	ds_read_b128 v[230:233], v188 offset:39936
	global_load_lds_dwordx4 v168, s[34:35]
	s_waitcnt vmcnt(8)
	s_waitcnt lgkmcnt(0)
	s_barrier
	v_mfma_f32_16x16x32_bf16 v[122:125], v[134:137], v[184:187], v[122:125]
	v_mfma_f32_16x16x32_bf16 v[122:125], v[138:141], v[190:193], v[122:125]
	v_mfma_f32_16x16x32_bf16 v[118:121], v[142:145], v[184:187], v[118:121]
	v_mfma_f32_16x16x32_bf16 v[118:121], v[146:149], v[190:193], v[118:121]
	v_mfma_f32_16x16x32_bf16 v[130:133], v[150:153], v[184:187], v[130:133]
	v_mfma_f32_16x16x32_bf16 v[130:133], v[154:157], v[190:193], v[130:133]
	v_mfma_f32_16x16x32_bf16 v[126:129], v[176:179], v[184:187], v[126:129]
	v_mfma_f32_16x16x32_bf16 v[126:129], v[180:183], v[190:193], v[126:129]
	v_mfma_f32_16x16x32_bf16 v[102:105], v[176:179], v[210:213], v[102:105]
	v_mfma_f32_16x16x32_bf16 v[102:105], v[180:183], v[214:217], v[102:105]
	v_mfma_f32_16x16x32_bf16 v[110:113], v[150:153], v[210:213], v[110:113]
	v_mfma_f32_16x16x32_bf16 v[110:113], v[154:157], v[214:217], v[110:113]
	v_mfma_f32_16x16x32_bf16 v[106:109], v[142:145], v[210:213], v[106:109]
	v_mfma_f32_16x16x32_bf16 v[106:109], v[146:149], v[214:217], v[106:109]
	v_mfma_f32_16x16x32_bf16 v[114:117], v[134:137], v[210:213], v[114:117]
	v_mfma_f32_16x16x32_bf16 v[114:117], v[138:141], v[214:217], v[114:117]
	v_mfma_f32_16x16x32_bf16 v[98:101], v[134:137], v[218:221], v[98:101]
	v_mfma_f32_16x16x32_bf16 v[98:101], v[138:141], v[222:225], v[98:101]
	v_mfma_f32_16x16x32_bf16 v[90:93], v[142:145], v[218:221], v[90:93]
	v_mfma_f32_16x16x32_bf16 v[90:93], v[146:149], v[222:225], v[90:93]
	v_mfma_f32_16x16x32_bf16 v[94:97], v[150:153], v[218:221], v[94:97]
	v_mfma_f32_16x16x32_bf16 v[94:97], v[154:157], v[222:225], v[94:97]
	v_mfma_f32_16x16x32_bf16 v[86:89], v[176:179], v[218:221], v[86:89]
	v_mfma_f32_16x16x32_bf16 v[86:89], v[180:183], v[222:225], v[86:89]
	v_mfma_f32_16x16x32_bf16 v[70:73], v[176:179], v[226:229], v[70:73]
	v_mfma_f32_16x16x32_bf16 v[70:73], v[180:183], v[230:233], v[70:73]
	v_mfma_f32_16x16x32_bf16 v[78:81], v[150:153], v[226:229], v[78:81]
	v_mfma_f32_16x16x32_bf16 v[78:81], v[154:157], v[230:233], v[78:81]
	v_mfma_f32_16x16x32_bf16 v[74:77], v[142:145], v[226:229], v[74:77]
	v_mfma_f32_16x16x32_bf16 v[74:77], v[146:149], v[230:233], v[74:77]
	v_mfma_f32_16x16x32_bf16 v[82:85], v[134:137], v[226:229], v[82:85]
	v_mfma_f32_16x16x32_bf16 v[82:85], v[138:141], v[230:233], v[82:85]
	s_barrier
	s_add_i32 s4, s24, 0x18000
	s_add_i32 m0, s4, 0xffffff80
	ds_read_b128 v[184:187], v188 offset:49152
	ds_read_b128 v[190:193], v188 offset:50176
	ds_read_b128 v[210:213], v188 offset:51200
	ds_read_b128 v[214:217], v188 offset:52224
	global_load_lds_dwordx4 v4, s[48:49] offset:128
	s_add_i32 m0, s4, 0x1f80
	s_add_u32 s34, s48, 0x80080
	s_addc_u32 s35, s49, 0
	s_add_i32 s4, s5, s24
	global_load_lds_dwordx4 v2, s[48:49] offset:128
	s_mov_b32 m0, s4
	ds_read_b128 v[218:221], v188 offset:53248
	global_load_lds_dwordx4 v4, s[34:35]
	s_add_i32 m0, s4, 0x2000
	ds_read_b128 v[222:225], v188 offset:54272
	global_load_lds_dwordx4 v2, s[34:35]
	s_add_i32 m0, s60, 0xffffff80
	ds_read_b128 v[226:229], v188 offset:55296
	global_load_lds_dwordx4 v170, s[52:53] offset:128
	s_add_i32 m0, s61, 0xffffff80
	ds_read_b128 v[230:233], v188 offset:56320
	global_load_lds_dwordx4 v168, s[52:53] offset:128
	s_waitcnt vmcnt(8)
	s_waitcnt lgkmcnt(0)
	s_barrier
	v_mfma_f32_16x16x32_bf16 v[58:61], v[134:137], v[184:187], v[58:61]
	v_mfma_f32_16x16x32_bf16 v[58:61], v[138:141], v[190:193], v[58:61]
	v_mfma_f32_16x16x32_bf16 v[54:57], v[142:145], v[184:187], v[54:57]
	v_mfma_f32_16x16x32_bf16 v[54:57], v[146:149], v[190:193], v[54:57]
	v_mfma_f32_16x16x32_bf16 v[66:69], v[150:153], v[184:187], v[66:69]
	v_mfma_f32_16x16x32_bf16 v[66:69], v[154:157], v[190:193], v[66:69]
	v_mfma_f32_16x16x32_bf16 v[62:65], v[176:179], v[184:187], v[62:65]
	v_mfma_f32_16x16x32_bf16 v[62:65], v[180:183], v[190:193], v[62:65]
	v_mfma_f32_16x16x32_bf16 v[38:41], v[176:179], v[210:213], v[38:41]
	v_mfma_f32_16x16x32_bf16 v[38:41], v[180:183], v[214:217], v[38:41]
	v_mfma_f32_16x16x32_bf16 v[46:49], v[150:153], v[210:213], v[46:49]
	v_mfma_f32_16x16x32_bf16 v[46:49], v[154:157], v[214:217], v[46:49]
	v_mfma_f32_16x16x32_bf16 v[42:45], v[142:145], v[210:213], v[42:45]
	v_mfma_f32_16x16x32_bf16 v[42:45], v[146:149], v[214:217], v[42:45]
	v_mfma_f32_16x16x32_bf16 v[50:53], v[134:137], v[210:213], v[50:53]
	v_mfma_f32_16x16x32_bf16 v[50:53], v[138:141], v[214:217], v[50:53]
	v_mfma_f32_16x16x32_bf16 v[34:37], v[134:137], v[218:221], v[34:37]
	v_mfma_f32_16x16x32_bf16 v[34:37], v[138:141], v[222:225], v[34:37]
	v_mfma_f32_16x16x32_bf16 v[26:29], v[142:145], v[218:221], v[26:29]
	v_mfma_f32_16x16x32_bf16 v[26:29], v[146:149], v[222:225], v[26:29]
	v_mfma_f32_16x16x32_bf16 v[30:33], v[150:153], v[218:221], v[30:33]
	v_mfma_f32_16x16x32_bf16 v[30:33], v[154:157], v[222:225], v[30:33]
	v_mfma_f32_16x16x32_bf16 v[22:25], v[176:179], v[218:221], v[22:25]
	v_mfma_f32_16x16x32_bf16 v[22:25], v[180:183], v[222:225], v[22:25]
	v_mfma_f32_16x16x32_bf16 v[6:9], v[176:179], v[226:229], v[6:9]
	v_mfma_f32_16x16x32_bf16 v[6:9], v[180:183], v[230:233], v[6:9]
	v_mfma_f32_16x16x32_bf16 v[14:17], v[150:153], v[226:229], v[14:17]
	v_mfma_f32_16x16x32_bf16 v[14:17], v[154:157], v[230:233], v[14:17]
	v_mfma_f32_16x16x32_bf16 v[10:13], v[142:145], v[226:229], v[10:13]
	v_mfma_f32_16x16x32_bf16 v[10:13], v[146:149], v[230:233], v[10:13]
	v_mfma_f32_16x16x32_bf16 v[18:21], v[134:137], v[226:229], v[18:21]
	v_mfma_f32_16x16x32_bf16 v[18:21], v[138:141], v[230:233], v[18:21]
	s_barrier
	s_add_i32 s20, s20, 2
	s_add_u32 s50, s50, 0x100
	s_addc_u32 s51, s51, 0
	s_add_u32 s69, s69, 0x100
	s_addc_u32 s71, s71, 0
	s_cmp_gt_u32 s20, 29
	s_cbranch_scc0 .LBB0_1738
	s_and_b64 vcc, exec, s[40:41]
	s_cbranch_vccz .LBB0_1741
	s_barrier
